# xbar2: grid barrier relay removed - all WG leaders poll monotonic TOP counter directly (no TOPGEN/XGEN hops)
# speedup vs baseline: 1.0041x; 1.0041x over previous
.LBB0_1260:
	v_readlane_b32 s2, v249, 5
	v_readlane_b32 s3, v249, 6
	s_and_b64 vcc, exec, s[2:3]
	s_cbranch_vccz .LBB0_1313
	s_mov_b32 s16, 1
	s_cmp_lt_i32 s16, 1
	s_cbranch_scc1 .LBB0_1312
	s_mov_b32 s17, 0
	s_branch .LBB0_1265
.LBB0_1264:
	s_or_b64 exec, exec, s[0:1]
	s_add_i32 s17, s17, 1
	s_cmp_eq_u32 s17, s16
	s_waitcnt lgkmcnt(0)
	s_barrier
	s_cbranch_scc1 .LBB0_1312

.LBB0_1281:
	v_readlane_b32 s2, v249, 61
	v_readlane_b32 s3, v249, 62
	v_cvt_f32_u32_e32 v1, v2
	v_sub_u32_e32 v4, 0, v2
	v_rcp_iflag_f32_e32 v1, v1
	s_nop 1
	global_atomic_add v3, v193, v216, s[2:3] sc0
	v_mul_f32_e32 v1, 0x4f7ffffe, v1
	v_cvt_u32_f32_e32 v1, v1
	v_mul_lo_u32 v4, v4, v1
	v_mul_hi_u32 v4, v1, v4
	v_add_u32_e32 v1, v1, v4
	s_waitcnt vmcnt(0)
	v_mul_hi_u32 v1, v3, v1
	v_mul_lo_u32 v4, v1, v2
	v_sub_u32_e32 v4, v3, v4
	v_add_u32_e32 v5, 1, v1
	v_cmp_ge_u32_e32 vcc, v4, v2
	v_add_u32_e32 v3, 1, v3
	s_nop 0
	v_cndmask_b32_e32 v1, v1, v5, vcc
	v_sub_u32_e32 v5, v4, v2
	v_cndmask_b32_e32 v4, v4, v5, vcc
	v_add_u32_e32 v5, 1, v1
	v_cmp_ge_u32_e32 vcc, v4, v2
	s_nop 1
	v_cndmask_b32_e32 v1, v1, v5, vcc
	v_mul_lo_u32 v4, v2, v1
	v_add_u32_e32 v2, v4, v2
	v_cmp_ne_u32_e32 vcc, v3, v2
	v_readlane_b32 s4, v250, 1
	v_readlane_b32 s5, v250, 2
	s_waitcnt lgkmcnt(0)
	v_add_u32_e32 v4, 1, v1
	v_mul_lo_u32 v4, v4, v0
	s_nop 3
	s_and_b64 vcc, exec, vcc
	s_cbranch_vccnz .Lxb_poll
	buffer_wbl2 sc1
	s_waitcnt vmcnt(0)
	global_atomic_add v193, v216, s[4:5]
.Lxb_poll:
	global_load_dword v5, v193, s[4:5] sc1
	s_waitcnt vmcnt(0)
	v_cmp_lt_u32_e32 vcc, v5, v4
	s_and_b64 vcc, exec, vcc
	s_cbranch_vccz .Lxb_done
	s_sleep 1
	s_branch .Lxb_poll
.Lxb_done:
	buffer_inv sc1
	s_waitcnt vmcnt(0)
	s_branch .LBB0_1264
